# late workgroups: SSD state/sample units assigned statically by workgroup id (no queue atomics) and cache K/V conversion with all loads in flight (measure 1)
# speedup vs baseline: 1.0056x; 1.0056x over previous
; __device__ __forceinline__ unsigned cvtpk(float lo, float hi) { unsigned r; asm volatile("v_cvt_pk_bf16_f32 %0, %1, %2" : "=v"(r) : "v"(lo), "v"(hi)); return r; }
; __device__ __forceinline__ void cache_mem_convert(const Params& p, int gt, int NGT) {
;     u32x4* cmk = (u32x4*)(p.ws + WS_CMK); u32x4* cmv = (u32x4*)(p.ws + WS_CMV);
;     constexpr int N8 = DSEQ * MEMT * 512 / 8;
;     for (int i = gt; i < 2 * N8; i += NGT) { const bool isk = i < N8; const int j = isk ? i : i - N8; const f32x4* s = (const f32x4*)(isk ? p.in[I_CMK] : p.in[I_CMV]) + 2 * (size_t)j;
;         const f32x4 a = s[0], b = s[1]; u32x4 o; o.x = cvtpk(a.x, a.y); o.y = cvtpk(a.z, a.w); o.z = cvtpk(b.x, b.y); o.w = cvtpk(b.z, b.w); (isk ? cmk : cmv)[j] = o; }
; }
.Lcmconv:
	s_lshl_b32 s7, s4, 1
	s_mul_i32 s8, s4, 3
	v_mov_b32_e32 v52, v1
	v_min_i32_e32 v52, s6, v52
	v_add_u32_e32 v2, 0xfffe0000, v52
	v_cmp_gt_i32_e32 vcc, s5, v52
	s_nop 1
	v_cndmask_b32_e32 v20, v2, v52, vcc
	v_ashrrev_i32_e32 v21, 31, v20
	v_cndmask_b32_e32 v55, v6, v7, vcc
	v_cndmask_b32_e32 v54, v8, v9, vcc
	v_lshlrev_b64 v[56:57], 5, v[20:21]
	v_lshl_add_u64 v[54:55], v[54:55], 0, v[56:57]
	global_load_dwordx4 v[10:13], v[54:55], off
	global_load_dwordx4 v[14:17], v[54:55], off offset:16
	v_cndmask_b32_e32 v2, v4, v5, vcc
	v_lshl_add_u64 v[58:59], s[90:91], 0, v[2:3]
	v_lshl_add_u64 v[18:19], v[20:21], 4, v[58:59]
	v_add_u32_e32 v52, s4, v1
	v_min_i32_e32 v52, s6, v52
	v_add_u32_e32 v2, 0xfffe0000, v52
	v_cmp_gt_i32_e32 vcc, s5, v52
	s_nop 1
	v_cndmask_b32_e32 v20, v2, v52, vcc
	v_ashrrev_i32_e32 v21, 31, v20
	v_cndmask_b32_e32 v55, v6, v7, vcc
	v_cndmask_b32_e32 v54, v8, v9, vcc
	v_lshlrev_b64 v[56:57], 5, v[20:21]
	v_lshl_add_u64 v[54:55], v[54:55], 0, v[56:57]
	global_load_dwordx4 v[22:25], v[54:55], off
	global_load_dwordx4 v[26:29], v[54:55], off offset:16
	v_cndmask_b32_e32 v2, v4, v5, vcc
	v_lshl_add_u64 v[58:59], s[90:91], 0, v[2:3]
	v_lshl_add_u64 v[46:47], v[20:21], 4, v[58:59]
	v_add_u32_e32 v52, s7, v1
	v_min_i32_e32 v52, s6, v52
	v_add_u32_e32 v2, 0xfffe0000, v52
	v_cmp_gt_i32_e32 vcc, s5, v52
	s_nop 1
	v_cndmask_b32_e32 v20, v2, v52, vcc
	v_ashrrev_i32_e32 v21, 31, v20
	v_cndmask_b32_e32 v55, v6, v7, vcc
	v_cndmask_b32_e32 v54, v8, v9, vcc
	v_lshlrev_b64 v[56:57], 5, v[20:21]
	v_lshl_add_u64 v[54:55], v[54:55], 0, v[56:57]
	global_load_dwordx4 v[30:33], v[54:55], off
	global_load_dwordx4 v[34:37], v[54:55], off offset:16
	v_cndmask_b32_e32 v2, v4, v5, vcc
	v_lshl_add_u64 v[58:59], s[90:91], 0, v[2:3]
	v_lshl_add_u64 v[48:49], v[20:21], 4, v[58:59]
	v_add_u32_e32 v52, s8, v1
	v_min_i32_e32 v52, s6, v52
	v_add_u32_e32 v2, 0xfffe0000, v52
	v_cmp_gt_i32_e32 vcc, s5, v52
	s_nop 1
	v_cndmask_b32_e32 v20, v2, v52, vcc
	v_ashrrev_i32_e32 v21, 31, v20
	v_cndmask_b32_e32 v55, v6, v7, vcc
	v_cndmask_b32_e32 v54, v8, v9, vcc
	v_lshlrev_b64 v[56:57], 5, v[20:21]
	v_lshl_add_u64 v[54:55], v[54:55], 0, v[56:57]
	global_load_dwordx4 v[38:41], v[54:55], off
	global_load_dwordx4 v[42:45], v[54:55], off offset:16
	v_cndmask_b32_e32 v2, v4, v5, vcc
	v_lshl_add_u64 v[58:59], s[90:91], 0, v[2:3]
	v_lshl_add_u64 v[50:51], v[20:21], 4, v[58:59]
	s_waitcnt vmcnt(6)
	v_cvt_pk_bf16_f32 v10, v10, v11
	v_cvt_pk_bf16_f32 v11, v12, v13
	v_cvt_pk_bf16_f32 v12, v14, v15
	v_cvt_pk_bf16_f32 v13, v16, v17
	s_waitcnt vmcnt(4)
	v_cvt_pk_bf16_f32 v22, v22, v23
	v_cvt_pk_bf16_f32 v23, v24, v25
	v_cvt_pk_bf16_f32 v24, v26, v27
	v_cvt_pk_bf16_f32 v25, v28, v29
	s_waitcnt vmcnt(2)
	v_cvt_pk_bf16_f32 v30, v30, v31
	v_cvt_pk_bf16_f32 v31, v32, v33
	v_cvt_pk_bf16_f32 v32, v34, v35
	v_cvt_pk_bf16_f32 v33, v36, v37
	s_waitcnt vmcnt(0)
	v_cvt_pk_bf16_f32 v38, v38, v39
	v_cvt_pk_bf16_f32 v39, v40, v41
	v_cvt_pk_bf16_f32 v40, v42, v43
	v_cvt_pk_bf16_f32 v41, v44, v45
	v_mov_b32_e32 v52, v1
	v_cmp_ge_i32_e32 vcc, s6, v52
	s_and_saveexec_b64 s[10:11], vcc
	s_cbranch_execz .Lcm_skip0
	global_store_dwordx4 v[18:19], v[10:13], off
.Lcm_skip0:
	s_mov_b64 exec, s[10:11]
	v_add_u32_e32 v52, s4, v1
	v_cmp_ge_i32_e32 vcc, s6, v52
	s_and_saveexec_b64 s[10:11], vcc
	s_cbranch_execz .Lcm_skip1
	global_store_dwordx4 v[46:47], v[22:25], off
.Lcm_skip1:
	s_mov_b64 exec, s[10:11]
	v_add_u32_e32 v52, s7, v1
	v_cmp_ge_i32_e32 vcc, s6, v52
	s_and_saveexec_b64 s[10:11], vcc
	s_cbranch_execz .Lcm_skip2
	global_store_dwordx4 v[48:49], v[30:33], off
.Lcm_skip2:
	s_mov_b64 exec, s[10:11]
	v_add_u32_e32 v52, s8, v1
	v_cmp_ge_i32_e32 vcc, s6, v52
	s_and_saveexec_b64 s[10:11], vcc
	s_cbranch_execz .Lcm_skip3
	global_store_dwordx4 v[50:51], v[38:41], off
.Lcm_skip3:
	s_mov_b64 exec, s[10:11]

; #define LAS __attribute__((address_space(3)))
; #define PSTAMP(i) do { if (PROBE_SEG >= 20 && blockIdx.x == PROBE_BLK && threadIdx.x == 0) ((volatile LAS unsigned long long*)(ctlw + 32))[8 + (i)] = __builtin_amdgcn_s_memrealtime(); } while (0)
; #define QUEUE_LOOP(qi, total, ...) for (;;) { __syncthreads(); if (threadIdx.x == 0) ctlw[16] = __hip_atomic_fetch_add(qbase + 64 * (qi), 1u, __ATOMIC_RELAXED, __HIP_MEMORY_SCOPE_AGENT); \
;         __syncthreads(); const int u = (int)ctlw[16]; if (u >= (total)) break; __VA_ARGS__ }
; template <int MASK> __device__ __forceinline__ void phase3(const Params& p, LAS unsigned char* lds, volatile LAS unsigned* ctlw, int qset) {
;     unsigned* qbase = (unsigned*)(p.ws + WS_CTL) + CW_QUEUE + 1024 * qset;
;     const bf16_t* PROJ = (const bf16_t*)(p.ws + WS_PROJ);
;     bf16_t* MIX = (bf16_t*)(p.ws + WS_MIX);
;     PSTAMP(4);
;     QUEUE_LOOP(0, U_SSDP, { ssd_state_unit<false>(p.ws, p.in[I_ALOG], p.in[I_SCONV], p.in[I_CONVW], p.in[I_CONVB], lds, u >> 5, (u >> 1) & 15, u & 1); })
.Lp3_enter:
	s_cmp_gt_i32 s6, 3
	s_cselect_b64 s[0:1], -1, 0
	s_cmp_lt_i32 s7, 4
	s_cselect_b64 s[2:3], -1, 0
	s_or_b64 s[0:1], s[0:1], s[2:3]
	s_and_b64 vcc, exec, s[0:1]
	v_mbcnt_lo_u32_b32 v190, -1, 0
	s_cbranch_vccnz .LBB0_1051
	s_add_u32 s48, s90, 0x5a00000
	s_addc_u32 s49, s91, 0
	s_add_u32 s12, s90, 0xd200000
	s_addc_u32 s13, s91, 0
	s_add_u32 s70, s90, 0x16200000
	s_addc_u32 s71, s91, 0
	s_add_u32 s14, s90, 0x13c00000
	s_addc_u32 s15, s91, 0
	s_add_u32 s72, s90, 0x14e00000
	s_addc_u32 s73, s91, 0
	s_add_i32 s24, 0, 0x27e40
	v_mbcnt_hi_u32_b32 v191, -1, v190
	s_waitcnt vmcnt(0)
	v_bfrev_b32_e32 v2, 0.5
	s_mov_b32 s5, 0
	v_cmp_eq_u32_e64 s[0:1], 0, v0
	v_mov_b32_e32 v155, 0
	s_movk_i32 s33, 0x3600
	s_movk_i32 s74, 0x2000
	s_mov_b64 s[6:7], 0x2400
	s_movk_i32 s75, 0x80
	s_mov_b64 s[8:9], 0x1800
	s_movk_i32 s76, 0x1000
	s_mov_b64 s[10:11], 0x2800
	s_mov_b64 s[16:17], 0x3800
	s_movk_i32 s77, 0x3000
	s_movk_i32 s78, 0x110
	s_mov_b64 s[18:19], 0x1c00
	s_mov_b64 s[20:21], 0x2c00
	s_mov_b64 s[22:23], 0x3c00
	s_mov_b64 s[26:27], 0x1000
	s_mov_b64 s[28:29], 0x2000
	s_mov_b64 s[30:31], 0x3000
	v_mov_b32_e32 v178, s24
	v_and_b32_e32 v192, 64, v191
	v_add_u32_e32 v1, -1, v191
	v_add_u32_e32 v180, -2, v191
	v_add_u32_e32 v181, -4, v191
	v_add_u32_e32 v182, -8, v191
	v_add_u32_e32 v183, -16, v191
	v_subrev_u32_e32 v184, 32, v191
	v_lshl_or_b32 v179, v191, 2, v2
	v_mov_b32_e32 v185, 0x8800
	v_mov_b32_e32 v186, 0x9900
	v_mov_b32_e32 v187, 0xaa00
	v_mov_b32_e32 v188, 0xbb00
	v_mov_b32_e32 v189, 0xcc00
	v_mov_b32_e32 v193, 0xdd00
	v_mov_b32_e32 v194, 0xee00
	v_mov_b32_e32 v195, 0xff00
	v_readlane_b32 s4, v254, 9
	s_cmpk_gt_i32 s4, 0x93
	s_cbranch_scc1 .LBB0_835
	s_min_u32 s99, s4, 0x80
	s_branch .LBB0_630

; #define QUEUE_LOOP(qi, total, ...) for (;;) { __syncthreads(); if (threadIdx.x == 0) ctlw[16] = __hip_atomic_fetch_add(qbase + 64 * (qi), 1u, __ATOMIC_RELAXED, __HIP_MEMORY_SCOPE_AGENT); \
;         __syncthreads(); const int u = (int)ctlw[16]; if (u >= (total)) break; __VA_ARGS__ }
; template <int MASK> __device__ __forceinline__ void phase3(const Params& p, LAS unsigned char* lds, volatile LAS unsigned* ctlw, int qset) {
;     ...
;     QUEUE_LOOP(0, U_SSDP, { ssd_state_unit<false>(p.ws, p.in[I_ALOG], p.in[I_SCONV], p.in[I_CONVW], p.in[I_CONVB], lds, u >> 5, (u >> 1) & 15, u & 1); })
.LBB0_630:
	s_barrier
	s_and_saveexec_b64 s[2:3], s[0:1]
	s_cbranch_execz .LBB0_634
	s_mov_b64 s[50:51], exec
	v_mbcnt_lo_u32_b32 v2, s50, 0
	v_mbcnt_hi_u32_b32 v2, s51, v2
	v_cmp_eq_u32_e32 vcc, 0, v2
	s_and_saveexec_b64 s[34:35], vcc
	s_cbranch_execz .LBB0_633
	s_bcnt1_i32_b64 s4, s[50:51]
	v_mov_b32_e32 v3, s99
	s_movk_i32 s99, 0x80

; #define QUEUE_LOOP(qi, total, ...) for (;;) { __syncthreads(); if (threadIdx.x == 0) ctlw[16] = __hip_atomic_fetch_add(qbase + 64 * (qi), 1u, __ATOMIC_RELAXED, __HIP_MEMORY_SCOPE_AGENT); \
;         __syncthreads(); const int u = (int)ctlw[16]; if (u >= (total)) break; __VA_ARGS__ }
; template <int MASK> __device__ __forceinline__ void phase3(const Params& p, LAS unsigned char* lds, volatile LAS unsigned* ctlw, int qset) {
;     ...
;     QUEUE_LOOP(4, U_SSDSS, { ssd_state_unit<true>(p.ws, p.in[I_ALOG], p.in[I_SCONV], p.in[I_CONVW], p.in[I_CONVB], lds, u >> 1, 0, u & 1);
;         for (int hh = 0; hh < 4; ++hh)
;             ssd_out_unit<true>(p.ws, p.out, p.in[I_ALOG], p.in[I_DSKIP], p.in[I_SSDNW], p.in[I_SSM], p.in[I_SCONV], p.in[I_CONVW], p.in[I_CONVB], lds, u >> 1, 0, (u & 1) * 4 + hh); })
.LBB0_679:
	v_readlane_b32 s4, v254, 9
	s_sub_i32 s4, s4, 0x80
	s_min_u32 s99, s4, 16
	s_add_i32 s66, 0, 0x27e40
	v_bfrev_b32_e32 v2, 0.5
	s_mov_b32 s17, 0
	v_mov_b32_e32 v155, 0
	v_mov_b32_e32 v185, s66
	s_movk_i32 s67, 0x2000
	v_bfrev_b32_e32 v157, 1
	s_movk_i32 s74, 0x3600
	s_movk_i32 s75, 0x3000
	s_mov_b64 s[18:19], 0x1000
	s_mov_b64 s[20:21], 0x2000
	s_mov_b64 s[22:23], 0x2400
	s_movk_i32 s76, 0x110
	s_mov_b64 s[26:27], 0x3000
	s_add_i32 s77, 0, 0x1e000
	s_add_i32 s78, 0, 0x1e200
	s_add_i32 s79, 0, 0x1e1fc
	s_add_i32 s84, 0, 0x11000
	s_mov_b32 s85, 0xe000000
	v_lshl_or_b32 v186, v191, 2, v2
	v_mov_b32_e32 v187, 0x3000
	v_mov_b32_e32 v188, 0x8800
	v_mov_b32_e32 v189, 0x9900
	v_mov_b32_e32 v193, 0xaa00
	v_mov_b32_e32 v194, 0xbb00
	v_mov_b32_e32 v195, 0xcc00
	v_mov_b32_e32 v196, 0xdd00
	v_mov_b32_e32 v197, 0xee00
	v_mov_b32_e32 v198, 0xff00
	s_branch .LBB0_682

; #define QUEUE_LOOP(qi, total, ...) for (;;) { __syncthreads(); if (threadIdx.x == 0) ctlw[16] = __hip_atomic_fetch_add(qbase + 64 * (qi), 1u, __ATOMIC_RELAXED, __HIP_MEMORY_SCOPE_AGENT); \
;         __syncthreads(); const int u = (int)ctlw[16]; if (u >= (total)) break; __VA_ARGS__ }
; template <int MASK> __device__ __forceinline__ void phase3(const Params& p, LAS unsigned char* lds, volatile LAS unsigned* ctlw, int qset) {
;     ...
;     QUEUE_LOOP(4, U_SSDSS, { ssd_state_unit<true>(p.ws, p.in[I_ALOG], p.in[I_SCONV], p.in[I_CONVW], p.in[I_CONVB], lds, u >> 1, 0, u & 1);
.LBB0_682:
	s_barrier
	s_and_saveexec_b64 s[2:3], s[0:1]
	s_cbranch_execz .LBB0_686
	s_mov_b64 s[6:7], exec
	v_mbcnt_lo_u32_b32 v2, s6, 0
	v_mbcnt_hi_u32_b32 v2, s7, v2
	v_cmp_eq_u32_e32 vcc, 0, v2
	s_and_saveexec_b64 s[4:5], vcc
	s_cbranch_execz .LBB0_685
	s_bcnt1_i32_b64 s6, s[6:7]
	s_waitcnt lgkmcnt(0)
	v_mov_b32_e32 v3, s99
	s_movk_i32 s99, 16
